# v30 + s5c item: loop-preheader vmcnt(0) after the d_skip load dropped (the quad is first read after the in-loop counted waits)
# baseline (speedup 1.0000x reference)
; __device__ __forceinline__ int otid() { int t = threadIdx.x; asm volatile("" : "+v"(t)); return t; }
; __device__ void s5c_item(const Params& p, int l, int item, LAS unsigned char* lds) {
;     const int xcd_ = item & 7, slot_ = (item >> 3) & 31, g = xcd_ * 4 + (slot_ & 3), span = (item >> 8) * 8 + (slot_ >> 2), mt0 = span * 8, nmt = span == 15 ? 9 : 8, iters = (nmt + 7) >> 3;
;     const int t = otid(), wave = t >> 6, lane = t & 63, fr = lane & 15, fq = lane >> 4;
;     bf16_t* proj = (bf16_t*)(p.ws + WS_PROJ);
;     const bf16_t* Wy = (const bf16_t*)(p.ws + WS_WY) + (size_t)g * 256 * 384;
;     const bf16_t* Tz = (const bf16_t*)(p.ws + WS_TZ) + (size_t)g * 16 * 512;
;     const float* Xin = (const float*)(p.ws + WS_XLOC);
;     const f32x4 dsk = *(const f32x4*)(p.d_skip + (size_t)l * 512 + g * 16 + 4 * fq);
;     for (int it = 0; it < iters; ++it) {
;         const int mt = mt0 + it * 8 + wave; const bool active = mt < mt0 + nmt;
;         u32x4 omf[8];
; #pragma unroll
;         for (int q = 0; q < 8; ++q) { const int i = t + 512 * q, r = i >> 4, c = i & 15; omf[q] = *(const u32x4*)(Wy + (size_t)r * 384 + 256 + c * 8); }
;         bf16x8 tf[16];
; #pragma unroll
;         for (int d = 0; d < 16; ++d) tf[d] = *(const bf16x8*)(Tz + d * 512 + fr * 32 + fq * 8);
.LBB0_523:
	s_and_b64 vcc, exec, s[10:11]
	s_cbranch_vccz .LBB0_448
	s_lshl_b32 s11, s29, 2
	s_and_b32 s11, s11, 28
	s_bfe_u32 s14, s29, 0x20003
	s_ashr_i32 s33, s29, 5
	s_bfe_u32 s10, s29, 0x30005
	s_or_b32 s23, s11, s14
	s_and_b32 s11, s33, -8
	s_lshl_b32 s22, s10, 3
	s_or_b32 s30, s11, s10
	s_cmp_eq_u32 s30, 15
	s_cselect_b32 s40, 9, 8
	s_lshl_b32 s42, s40, 8
	s_mul_i32 s10, s23, 0x30000
	s_add_u32 s10, s36, s10
	s_waitcnt vmcnt(0)
	v_mov_b32_e32 v14, v228
	s_addc_u32 s11, s37, 0
	s_lshl_b32 s14, s23, 6
	s_add_u32 s14, s12, s14
	v_bfe_u32 v11, v14, 4, 2
	s_addc_u32 s15, s13, 0
	s_waitcnt lgkmcnt(0)
	v_lshlrev_b32_e32 v6, 4, v11
	global_load_dwordx4 v[2:5], v6, s[14:15]
	s_lshl_b32 s14, s23, 14
	v_and_b32_e32 v16, 15, v14
	s_add_u32 s14, s79, s14
	s_addc_u32 s15, s80, 0
	s_lshl_b32 s30, s30, 3
	v_lshlrev_b32_e32 v0, 6, v16
	s_add_i32 s30, s40, s30
	v_lshl_add_u64 v[8:9], s[14:15], 0, v[0:1]
	s_lshl_b32 s14, s23, 5
	s_add_u32 s14, s20, s14
	v_mov_b32_e32 v7, v1
	s_addc_u32 s15, s21, 0
	s_lshl_b32 s23, s23, 9
	v_lshl_add_u64 v[150:151], v[8:9], 0, v[6:7]
	v_and_b32_e32 v8, 16, v14
	v_mov_b32_e32 v9, v1
	s_add_u32 s40, s73, s23
	v_lshrrev_b32_e32 v10, 4, v14
	v_lshlrev_b32_e32 v0, 3, v11
	v_lshl_add_u64 v[152:153], s[14:15], 0, v[8:9]
	s_addc_u32 s41, s78, 0
	v_lshlrev_b32_e32 v8, 5, v11
	v_bfe_u32 v17, v10, 1, 1
	v_lshl_add_u64 v[154:155], s[40:41], 0, v[8:9]
	v_lshlrev_b32_e32 v8, 4, v14
	v_lshl_add_u64 v[156:157], s[14:15], 0, v[0:1]
	v_ashrrev_i32_e32 v0, 4, v14
	v_mov_b64_e32 v[10:11], s[10:11]
	v_and_b32_e32 v8, 0xf0, v8
	v_mad_i64_i32 v[12:13], s[10:11], v0, s38, v[10:11]
	v_lshl_add_u64 v[12:13], v[12:13], 0, v[8:9]
	s_mov_b64 s[14:15], 0x1d0f0200
	v_lshl_add_u64 v[158:159], v[12:13], 0, s[14:15]
	v_add_u32_e32 v12, 0x200, v14
	v_ashrrev_i32_e32 v19, 4, v12
	v_mad_i64_i32 v[12:13], s[10:11], v19, s38, v[10:11]
	v_lshl_add_u64 v[12:13], v[12:13], 0, v[8:9]
	v_lshl_add_u64 v[160:161], v[12:13], 0, s[14:15]
	v_add_u32_e32 v12, 0x400, v14
	v_ashrrev_i32_e32 v20, 4, v12
	v_mad_i64_i32 v[12:13], s[10:11], v20, s38, v[10:11]
	v_lshl_add_u64 v[12:13], v[12:13], 0, v[8:9]
	v_lshl_add_u64 v[162:163], v[12:13], 0, s[14:15]
	v_add_u32_e32 v12, 0x600, v14
	v_ashrrev_i32_e32 v21, 4, v12
	v_mad_i64_i32 v[12:13], s[10:11], v21, s38, v[10:11]
	v_lshl_add_u64 v[12:13], v[12:13], 0, v[8:9]
	v_lshl_add_u64 v[164:165], v[12:13], 0, s[14:15]
	v_add_u32_e32 v12, 0x800, v14
	v_ashrrev_i32_e32 v22, 4, v12
	v_mad_i64_i32 v[12:13], s[10:11], v22, s38, v[10:11]
	v_lshl_add_u64 v[12:13], v[12:13], 0, v[8:9]
	v_lshl_add_u64 v[166:167], v[12:13], 0, s[14:15]
	v_add_u32_e32 v12, 0xa00, v14
	v_ashrrev_i32_e32 v23, 4, v12
	v_mad_i64_i32 v[12:13], s[10:11], v23, s38, v[10:11]
	v_lshl_add_u64 v[12:13], v[12:13], 0, v[8:9]
	v_lshl_add_u64 v[168:169], v[12:13], 0, s[14:15]
	v_add_u32_e32 v12, 0xc00, v14
	v_ashrrev_i32_e32 v24, 4, v12
	v_mad_i64_i32 v[12:13], s[10:11], v24, s38, v[10:11]
	v_lshl_add_u64 v[12:13], v[12:13], 0, v[8:9]
	v_lshl_add_u64 v[170:171], v[12:13], 0, s[14:15]
	v_add_u32_e32 v12, 0xe00, v14
	v_ashrrev_i32_e32 v12, 4, v12
	v_mad_i64_i32 v[10:11], s[10:11], v12, s38, v[10:11]
	s_mov_b64 s[10:11], 0x1000
	s_nop 0
	v_lshl_add_u64 v[174:175], v[150:151], 0, s[10:11]
	s_mov_b64 s[10:11], 0x1400
	v_lshl_add_u64 v[176:177], v[150:151], 0, s[10:11]
	s_mov_b64 s[10:11], 0x1800
	v_lshl_add_u64 v[178:179], v[150:151], 0, s[10:11]
	s_mov_b64 s[10:11], 0x1c00
	v_lshl_add_u64 v[180:181], v[150:151], 0, s[10:11]
	s_mov_b64 s[10:11], 0x2000
	v_lshl_add_u64 v[182:183], v[150:151], 0, s[10:11]
	s_mov_b64 s[10:11], 0x2400
	v_lshl_add_u64 v[184:185], v[150:151], 0, s[10:11]
	s_mov_b64 s[10:11], 0x2800
	v_lshl_add_u64 v[186:187], v[150:151], 0, s[10:11]
	s_mov_b64 s[10:11], 0x2c00
	v_lshl_add_u64 v[188:189], v[150:151], 0, s[10:11]
	s_mov_b64 s[10:11], 0x3000
	v_lshl_add_u64 v[190:191], v[150:151], 0, s[10:11]
	s_mov_b64 s[10:11], 0x3400
	v_lshl_add_u64 v[192:193], v[150:151], 0, s[10:11]
	s_mov_b64 s[10:11], 0x3800
	v_lshl_add_u64 v[194:195], v[150:151], 0, s[10:11]
	s_mov_b64 s[10:11], 0x3c00
	v_add_u32_e32 v18, 0, v8
	v_lshl_add_u64 v[8:9], v[10:11], 0, v[8:9]
	v_lshl_add_u64 v[202:203], v[150:151], 0, s[10:11]
	s_movk_i32 s10, 0x110
	v_ashrrev_i32_e32 v15, 6, v14
	v_lshl_add_u64 v[172:173], v[8:9], 0, s[14:15]
	v_mul_lo_u32 v8, v0, s10
	v_mul_lo_u32 v9, v19, s10
	v_mul_lo_u32 v10, v20, s10
	v_mul_lo_u32 v11, v21, s10
	v_mul_lo_u32 v13, v22, s10
	v_mul_lo_u32 v14, v23, s10
	v_mul_lo_u32 v19, v24, s10
	v_mul_lo_u32 v12, v12, s10
	s_lshl_b32 s10, s33, 3
	s_andn2_b32 s10, s10, 63
	s_or_b32 s10, s22, s10
	v_lshlrev_b32_e32 v7, 4, v16
	v_add_u32_e32 v208, s10, v15
	v_mul_u32_u24_e32 v0, 0x110, v16
	s_addk_i32 s42, 0x700
	v_lshl_or_b32 v209, v208, 8, v7
	v_add3_u32 v0, 0, v6, v0
	s_and_b32 s40, s42, 0x1800
	v_or_b32_e32 v210, v209, v17
	v_lshl_or_b32 v204, v208, 4, v16
	s_mov_b32 s41, 0
	v_add_u32_e32 v211, v18, v8
	v_add_u32_e32 v212, v18, v9
	v_add_u32_e32 v213, v18, v10
	v_add_u32_e32 v214, v18, v11
	v_add_u32_e32 v215, v18, v13
	v_add_u32_e32 v216, v18, v14
	v_add_u32_e32 v217, v18, v19
	v_add_u32_e32 v218, v18, v12
	s_branch .LBB0_526
